# residual fragments' staging DMAs (fused P6, P4 final tile) nontemporal: once-read data
# baseline (speedup 1.0000x reference)
;     __device__ __forceinline__ void operator()(const f32x4 (&acc)[2][2][4][2], const Unit& u, int wr, int wc, int fr, int fq) const {
;     ...
;             for (int m = 0; m < 4; ++m) { const size_t off = (size_t)(row0 + ai * HALF + m * 16) * ldc + col0;
; #pragma unroll
;                 for (int bj = 0; bj < 2; ++bj) bv[ai][m][bj] = __builtin_nontemporal_load((const u32x4*)(xb + off + bj * HALF)); }
mk_p4_chk:
	s_cmp_lg_u64 s[4:5], 0
	s_cbranch_scc0 .LBB0_623
	v_readlane_b32 s98, v254, 20
	v_readlane_b32 s99, v254, 21
	s_lshl_b32 s100, s15, 8
	s_add_i32 s100, s100, s48
	s_lshl_b32 s100, s100, 12
	s_lshl_b32 s101, s14, 8
	s_or_b32 s101, s101, s50
	s_lshl_b32 s101, s101, 1
	s_add_u32 s100, s100, s101
	s_nop 3
	s_add_u32 s98, s98, s100
	s_addc_u32 s99, s99, 0
	s_add_u32 s100, s98, 0x100
	s_addc_u32 s101, s99, 0
	v_mbcnt_lo_u32_b32 v186, -1, 0
	v_mbcnt_hi_u32_b32 v186, -1, v186
	v_and_b32_e32 v190, 15, v186
	v_lshrrev_b32_e32 v186, 4, v186
	v_lshlrev_b32_e32 v186, 4, v186
	v_lshl_or_b32 v186, v190, 12, v186
	s_add_u32 s6, s20, 0x100
	s_addc_u32 s7, s21, 0
	s_cmp_eq_u32 s59, 20
	s_cselect_b32 s24, s10, s6
	s_cselect_b32 s25, s11, s7
	s_cselect_b32 s27, s13, s58
	s_cselect_b32 s26, s12, s55
	s_add_u32 s16, s24, 0x80
	s_addc_u32 s17, s25, 0
	s_add_u32 s18, s26, 0x80
	s_addc_u32 s19, s27, 0
	s_add_u32 s60, s20, 0x60080
	s_addc_u32 s61, s21, 0
	s_add_u32 s22, s24, 0x60000
	s_addc_u32 s23, s25, 0
	s_add_u32 s28, s26, 0x60000
	s_addc_u32 s29, s27, 0
	s_add_u32 s20, s26, 0x60080
	s_addc_u32 s21, s27, 0
	ds_read_b128 v[130:133], v187
	ds_read_b128 v[134:137], v187 offset:1024
	ds_read_b128 v[138:141], v187 offset:2048
	ds_read_b128 v[142:145], v187 offset:3072
	ds_read_b128 v[146:149], v189
	ds_read_b128 v[150:153], v189 offset:1024
	ds_read_b128 v[154:157], v189 offset:2048
	ds_read_b128 v[158:161], v189 offset:3072
	s_mov_b32 m0, s47
	ds_read_b128 v[162:165], v191
	ds_read_b128 v[166:169], v191 offset:1024
	ds_read_b128 v[170:173], v191 offset:2048
	ds_read_b128 v[174:177], v191 offset:3072
	ds_read_b128 v[196:199], v191 offset:4096
	ds_read_b128 v[200:203], v191 offset:5120
	ds_read_b128 v[204:207], v191 offset:6144
	ds_read_b128 v[208:211], v191 offset:7168
	global_load_lds_dwordx4 v184, s[60:61]
	s_mov_b32 m0, s49
	s_nop 0
	global_load_lds_dwordx4 v188, s[60:61]
	s_waitcnt vmcnt(8)
	s_waitcnt lgkmcnt(0)
	s_barrier
	s_setprio 1
	s_waitcnt lgkmcnt(0)
	v_mfma_f32_16x16x128_f8f6f4 v[124:127], v[130:137], v[162:169], v[124:127]
	v_mfma_f32_16x16x128_f8f6f4 v[120:123], v[138:145], v[162:169], v[120:123]
	v_mfma_f32_16x16x128_f8f6f4 v[108:111], v[130:137], v[170:177], v[108:111]
	v_mfma_f32_16x16x128_f8f6f4 v[104:107], v[138:145], v[170:177], v[104:107]
	v_mfma_f32_16x16x128_f8f6f4 v[178:181], v[130:137], v[196:203], v[92:95]
	v_mfma_f32_16x16x128_f8f6f4 v[216:219], v[138:145], v[196:203], v[88:91]
	v_mfma_f32_16x16x128_f8f6f4 v[220:223], v[130:137], v[204:211], v[76:79]
	v_mfma_f32_16x16x128_f8f6f4 v[224:227], v[138:145], v[204:211], v[72:75]
	s_setprio 0
	s_setprio 1
	v_mfma_f32_16x16x128_f8f6f4 v[116:119], v[146:153], v[162:169], v[116:119]
	v_mfma_f32_16x16x128_f8f6f4 v[112:115], v[154:161], v[162:169], v[112:115]
	v_mfma_f32_16x16x128_f8f6f4 v[100:103], v[146:153], v[170:177], v[100:103]
	v_mfma_f32_16x16x128_f8f6f4 v[96:99], v[154:161], v[170:177], v[96:99]
	v_mfma_f32_16x16x128_f8f6f4 v[162:165], v[146:153], v[196:203], v[84:87]
	v_mfma_f32_16x16x128_f8f6f4 v[166:169], v[154:161], v[196:203], v[80:83]
	v_mfma_f32_16x16x128_f8f6f4 v[170:173], v[146:153], v[204:211], v[68:71]
	v_mfma_f32_16x16x128_f8f6f4 v[174:177], v[154:161], v[204:211], v[64:67]
	s_setprio 0
	s_barrier
	s_mov_b32 m0, s51
	s_nop 3
	ds_read_b128 v[64:67], v191 offset:16384
	ds_read_b128 v[68:71], v191 offset:17408
	ds_read_b128 v[72:75], v191 offset:18432
	ds_read_b128 v[76:79], v191 offset:19456
	ds_read_b128 v[80:83], v191 offset:20480
	ds_read_b128 v[84:87], v191 offset:21504
	ds_read_b128 v[88:91], v191 offset:22528
	ds_read_b128 v[92:95], v191 offset:23552
	global_load_lds_dwordx4 v186, s[98:99] nt
	s_mov_b32 m0, s52
	s_nop 0
	global_load_lds_dwordx4 v186, s[100:101] nt
	s_mov_b32 m0, s53
	s_nop 0
	s_add_u32 s98, s98, 0x10000
	s_addc_u32 s99, s99, 0
	s_add_u32 s100, s100, 0x10000
	s_addc_u32 s101, s101, 0
	global_load_lds_dwordx4 v186, s[98:99] nt
	s_mov_b32 m0, s54
	s_nop 0
	global_load_lds_dwordx4 v186, s[100:101] nt
	s_mov_b32 m0, s34
	s_nop 0
	s_add_u32 s98, s98, 0x10000
	s_addc_u32 s99, s99, 0
	s_add_u32 s100, s100, 0x10000
	s_addc_u32 s101, s101, 0
	global_load_lds_dwordx4 v186, s[98:99] nt
	s_mov_b32 m0, s35
	s_nop 0
	global_load_lds_dwordx4 v186, s[100:101] nt
	s_waitcnt vmcnt(8)
	s_waitcnt lgkmcnt(0)
	s_barrier
	s_setprio 1
	s_waitcnt lgkmcnt(0)
	v_mfma_f32_16x16x128_f8f6f4 v[60:63], v[130:137], v[64:71], v[60:63]
	v_mfma_f32_16x16x128_f8f6f4 v[56:59], v[138:145], v[64:71], v[56:59]
	v_mfma_f32_16x16x128_f8f6f4 v[196:199], v[130:137], v[72:79], v[44:47]
	v_mfma_f32_16x16x128_f8f6f4 v[200:203], v[138:145], v[72:79], v[40:43]
	v_mfma_f32_16x16x128_f8f6f4 v[204:207], v[130:137], v[80:87], v[28:31]
	v_mfma_f32_16x16x128_f8f6f4 v[208:211], v[138:145], v[80:87], v[24:27]
	v_mfma_f32_16x16x128_f8f6f4 v[228:231], v[130:137], v[88:95], v[12:15]
	v_mfma_f32_16x16x128_f8f6f4 v[232:235], v[138:145], v[88:95], v[8:11]
	s_setprio 0
	s_setprio 1
	v_mfma_f32_16x16x128_f8f6f4 v[52:55], v[146:153], v[64:71], v[52:55]
	v_mfma_f32_16x16x128_f8f6f4 v[48:51], v[154:161], v[64:71], v[48:51]
	v_mfma_f32_16x16x128_f8f6f4 v[236:239], v[146:153], v[72:79], v[36:39]
	v_mfma_f32_16x16x128_f8f6f4 v[240:243], v[154:161], v[72:79], v[32:35]
	v_mfma_f32_16x16x128_f8f6f4 v[244:247], v[146:153], v[80:87], v[20:23]
	v_mfma_f32_16x16x128_f8f6f4 v[248:251], v[154:161], v[80:87], v[16:19]
	v_mfma_f32_16x16x128_f8f6f4 v[192:195], v[146:153], v[88:95], v[4:7]
	v_mfma_f32_16x16x128_f8f6f4 v[212:215], v[154:161], v[88:95], v[0:3]
	s_setprio 0
	s_barrier
;     __device__ __forceinline__ void operator()(const f32x4 (&acc)[2][2][4][2], const Unit& u, int wr, int wc, int fr, int fq) const {
;     ...
;             for (int m = 0; m < 4; ++m) { const size_t off = (size_t)(row0 + ai * HALF + m * 16) * ldc + col0;
; #pragma unroll
;                 for (int bj = 0; bj < 2; ++bj) bv[ai][m][bj] = __builtin_nontemporal_load((const u32x4*)(xb + off + bj * HALF)); }
	s_nop 4
	ds_read_b128 v[0:3], v128
	ds_read_b128 v[4:7], v128 offset:1024
	ds_read_b128 v[16:19], v128 offset:2048
	ds_read_b128 v[20:23], v128 offset:3072
	ds_read_b128 v[130:133], v129
	ds_read_b128 v[134:137], v129 offset:1024
	ds_read_b128 v[138:141], v129 offset:2048
	ds_read_b128 v[142:145], v129 offset:3072
	s_mov_b32 m0, s36
	ds_read_b128 v[8:11], v191 offset:32768
	ds_read_b128 v[12:15], v191 offset:33792
	ds_read_b128 v[24:27], v191 offset:34816
	ds_read_b128 v[28:31], v191 offset:35840
	ds_read_b128 v[32:35], v191 offset:36864
	ds_read_b128 v[36:39], v191 offset:37888
	ds_read_b128 v[40:43], v191 offset:38912
	ds_read_b128 v[44:47], v191 offset:39936
	s_add_u32 s98, s98, 0x10000
	s_addc_u32 s99, s99, 0
	s_add_u32 s100, s100, 0x10000
	s_addc_u32 s101, s101, 0
	global_load_lds_dwordx4 v186, s[98:99] nt
	s_mov_b32 m0, s37
	s_nop 0
	global_load_lds_dwordx4 v186, s[100:101] nt
	s_waitcnt vmcnt(8)
	s_waitcnt lgkmcnt(0)
	s_barrier
	s_setprio 1
	s_waitcnt lgkmcnt(0)
	v_mfma_f32_16x16x128_f8f6f4 v[124:127], v[0:7], v[8:15], v[124:127]
	v_mfma_f32_16x16x128_f8f6f4 v[120:123], v[16:23], v[8:15], v[120:123]
	v_mfma_f32_16x16x128_f8f6f4 v[108:111], v[0:7], v[24:31], v[108:111]
	v_mfma_f32_16x16x128_f8f6f4 v[104:107], v[16:23], v[24:31], v[104:107]
	v_mfma_f32_16x16x128_f8f6f4 v[92:95], v[0:7], v[32:39], v[178:181]
	v_mfma_f32_16x16x128_f8f6f4 v[88:91], v[16:23], v[32:39], v[216:219]
	v_mfma_f32_16x16x128_f8f6f4 v[76:79], v[0:7], v[40:47], v[220:223]
	v_mfma_f32_16x16x128_f8f6f4 v[72:75], v[16:23], v[40:47], v[224:227]
	s_setprio 0
	s_setprio 1
	v_mfma_f32_16x16x128_f8f6f4 v[116:119], v[130:137], v[8:15], v[116:119]
	v_mfma_f32_16x16x128_f8f6f4 v[112:115], v[138:145], v[8:15], v[112:115]
	v_mfma_f32_16x16x128_f8f6f4 v[100:103], v[130:137], v[24:31], v[100:103]
	v_mfma_f32_16x16x128_f8f6f4 v[96:99], v[138:145], v[24:31], v[96:99]
	v_mfma_f32_16x16x128_f8f6f4 v[84:87], v[130:137], v[32:39], v[162:165]
	v_mfma_f32_16x16x128_f8f6f4 v[80:83], v[138:145], v[32:39], v[166:169]
	v_mfma_f32_16x16x128_f8f6f4 v[68:71], v[130:137], v[40:47], v[170:173]
	v_mfma_f32_16x16x128_f8f6f4 v[64:67], v[138:145], v[40:47], v[174:177]
	s_setprio 0
	s_barrier
	s_mov_b32 m0, s30
	ds_read_b128 v[32:35], v191 offset:49152
	ds_read_b128 v[36:39], v191 offset:50176
	ds_read_b128 v[146:149], v191 offset:51200
	ds_read_b128 v[150:153], v191 offset:52224
	ds_read_b128 v[154:157], v191 offset:53248
	ds_read_b128 v[158:161], v191 offset:54272
	ds_read_b128 v[162:165], v191 offset:55296
	ds_read_b128 v[166:169], v191 offset:56320
	s_add_u32 s98, s98, 0x50000
	s_addc_u32 s99, s99, 0
	s_add_u32 s100, s100, 0x50000
	s_addc_u32 s101, s101, 0
	global_load_lds_dwordx4 v186, s[98:99] nt
	s_mov_b32 m0, s31
	s_nop 0
	global_load_lds_dwordx4 v186, s[100:101] nt
	s_mov_b32 m0, s56
	s_nop 0
	s_add_u32 s98, s98, 0x10000
	s_addc_u32 s99, s99, 0
	s_add_u32 s100, s100, 0x10000
	s_addc_u32 s101, s101, 0
	global_load_lds_dwordx4 v186, s[98:99] nt
	s_mov_b32 m0, s57
	s_nop 0
	global_load_lds_dwordx4 v186, s[100:101] nt
	s_mov_b32 m0, s39
	s_nop 0
	s_add_u32 s98, s98, 0x10000
	s_addc_u32 s99, s99, 0
	s_add_u32 s100, s100, 0x10000
	s_addc_u32 s101, s101, 0
	global_load_lds_dwordx4 v186, s[98:99] nt
	s_mov_b32 m0, s40
	s_nop 0
	global_load_lds_dwordx4 v186, s[100:101] nt
	s_waitcnt vmcnt(8)
	s_waitcnt lgkmcnt(0)
	s_barrier
	s_setprio 1
	s_waitcnt lgkmcnt(0)
	v_mfma_f32_16x16x128_f8f6f4 v[60:63], v[0:7], v[32:39], v[60:63]
	v_mfma_f32_16x16x128_f8f6f4 v[56:59], v[16:23], v[32:39], v[56:59]
	v_mfma_f32_16x16x128_f8f6f4 v[44:47], v[0:7], v[146:153], v[196:199]
	v_mfma_f32_16x16x128_f8f6f4 v[40:43], v[16:23], v[146:153], v[200:203]
	v_mfma_f32_16x16x128_f8f6f4 v[28:31], v[0:7], v[154:161], v[204:207]
	v_mfma_f32_16x16x128_f8f6f4 v[24:27], v[16:23], v[154:161], v[208:211]
	v_mfma_f32_16x16x128_f8f6f4 v[12:15], v[0:7], v[162:169], v[228:231]
	v_mfma_f32_16x16x128_f8f6f4 v[8:11], v[16:23], v[162:169], v[232:235]
	s_setprio 0
	s_setprio 1
	v_mfma_f32_16x16x128_f8f6f4 v[52:55], v[130:137], v[32:39], v[52:55]
	v_mfma_f32_16x16x128_f8f6f4 v[48:51], v[138:145], v[32:39], v[48:51]
	v_mfma_f32_16x16x128_f8f6f4 v[36:39], v[130:137], v[146:153], v[236:239]
	v_mfma_f32_16x16x128_f8f6f4 v[32:35], v[138:145], v[146:153], v[240:243]
	v_mfma_f32_16x16x128_f8f6f4 v[20:23], v[130:137], v[154:161], v[244:247]
	v_mfma_f32_16x16x128_f8f6f4 v[16:19], v[138:145], v[154:161], v[248:251]
	v_mfma_f32_16x16x128_f8f6f4 v[4:7], v[130:137], v[162:169], v[192:195]
	v_mfma_f32_16x16x128_f8f6f4 v[0:3], v[138:145], v[162:169], v[212:215]
	s_setprio 0
	s_barrier
	s_add_u32 s98, s98, 0x10000
	s_addc_u32 s99, s99, 0
	s_add_u32 s100, s100, 0x10000
	s_addc_u32 s101, s101, 0
	s_mov_b32 m0, s47
	s_nop 0
	global_load_lds_dwordx4 v186, s[98:99] nt
	s_mov_b32 m0, s49
	s_nop 0
	global_load_lds_dwordx4 v186, s[100:101] nt
	s_add_i32 s59, s59, 2
	s_add_u32 s55, s55, 0x100
	s_addc_u32 s58, s58, 0
	s_mov_b64 s[20:21], s[6:7]

;     __device__ __forceinline__ void operator()(f32x4 (&acc)[2][2][4][2], const Unit& u, int wr, int wc, int fr, int fq) const {
;     ...
;                 for (int m = 0; m < 4; ++m) { const size_t off = (size_t)(row0 + ai * HALF + m * 16) * ldc + col0;
; #pragma unroll
;                     for (int bj = 0; bj < 2; ++bj) bv[ai][m][bj] = __builtin_nontemporal_load((const u32x4*)(hb + off + bj * HALF)); }
mk_p6_last:
	s_lshl_b32 s98, s75, 8
	s_add_i32 s98, s98, s48
	s_lshl_b32 s98, s98, 12
	s_lshl_b32 s99, s74, 8
	s_or_b32 s99, s99, s50
	s_lshl_b32 s99, s99, 1
	s_add_u32 s98, s98, s99
	s_add_u32 s98, s30, s98
	s_addc_u32 s99, s31, 0
	s_add_u32 s100, s98, 0x100
	s_addc_u32 s101, s99, 0
	v_mbcnt_lo_u32_b32 v249, -1, 0
	v_mbcnt_hi_u32_b32 v249, -1, v249
	v_and_b32_e32 v248, 15, v249
	v_lshrrev_b32_e32 v249, 4, v249
	v_lshlrev_b32_e32 v249, 4, v249
	v_lshl_or_b32 v249, v248, 12, v249
	s_add_u32 s42, s20, 0x100
	s_addc_u32 s43, s21, 0
	s_cmpk_eq_i32 s89, 0x7c
	s_cselect_b32 s28, s86, s42
	s_cselect_b32 s29, s81, s43
	s_cselect_b32 s23, s37, s88
	s_cselect_b32 s22, s87, vcc_lo
	s_add_u32 s26, s28, 0x80
	s_addc_u32 s27, s29, 0
	s_add_u32 s66, s22, 0x80
	s_addc_u32 s67, s23, 0
	s_add_u32 s90, s20, 0x200080
	s_addc_u32 s91, s21, 0
	s_add_u32 s52, s28, 0x200000
	s_addc_u32 s53, s29, 0
	s_add_u32 s56, s22, 0x200000
	s_addc_u32 s57, s23, 0
	s_add_u32 s20, s22, 0x200080
	s_addc_u32 s21, s23, 0
	s_add_i32 s92, 0, 0x10000
	s_add_i32 s93, 0, 0x14000
	v_add_u32_e32 v140, s92, v203
	v_add_u32_e32 v156, s93, v203
	ds_read_b128 v[128:131], v140
	ds_read_b128 v[132:135], v140 offset:1024
	ds_read_b128 v[136:139], v140 offset:2048
	ds_read_b128 v[140:143], v140 offset:3072
	ds_read_b128 v[144:147], v156
	ds_read_b128 v[148:151], v156 offset:1024
	ds_read_b128 v[152:155], v156 offset:2048
	ds_read_b128 v[156:159], v156 offset:3072
	s_add_i32 m0, s73, 0xc000
	ds_read_b128 v[160:163], v205
	ds_read_b128 v[164:167], v205 offset:1024
	ds_read_b128 v[168:171], v205 offset:2048
	ds_read_b128 v[172:175], v205 offset:3072
	ds_read_b128 v[176:179], v205 offset:4096
	ds_read_b128 v[180:183], v205 offset:5120
	ds_read_b128 v[184:187], v205 offset:6144
	ds_read_b128 v[188:191], v205 offset:7168
	global_load_lds_dwordx4 v202, s[90:91]
	s_add_i32 m0, s73, 0xe000
	s_nop 0
	global_load_lds_dwordx4 v204, s[90:91]
	s_waitcnt vmcnt(8)
	s_waitcnt lgkmcnt(0)
	s_barrier
	s_setprio 1
	s_waitcnt lgkmcnt(0)
	v_mfma_f32_16x16x32_bf16 v[124:127], v[128:131], v[160:163], v[124:127]
	v_mfma_f32_16x16x32_bf16 v[120:123], v[136:139], v[160:163], v[120:123]
	v_mfma_f32_16x16x32_bf16 v[108:111], v[128:131], v[168:171], v[108:111]
	v_mfma_f32_16x16x32_bf16 v[104:107], v[136:139], v[168:171], v[104:107]
	v_mfma_f32_16x16x32_bf16 v[92:95], v[128:131], v[176:179], v[92:95]
	v_mfma_f32_16x16x32_bf16 v[88:91], v[136:139], v[176:179], v[88:91]
	v_mfma_f32_16x16x32_bf16 v[76:79], v[128:131], v[184:187], v[76:79]
	v_mfma_f32_16x16x32_bf16 v[72:75], v[136:139], v[184:187], v[72:75]
	v_mfma_f32_16x16x32_bf16 v[124:127], v[132:135], v[164:167], v[124:127]
	v_mfma_f32_16x16x32_bf16 v[120:123], v[140:143], v[164:167], v[120:123]
	v_mfma_f32_16x16x32_bf16 v[108:111], v[132:135], v[172:175], v[108:111]
	v_mfma_f32_16x16x32_bf16 v[104:107], v[140:143], v[172:175], v[104:107]
	v_mfma_f32_16x16x32_bf16 v[92:95], v[132:135], v[180:183], v[92:95]
	v_mfma_f32_16x16x32_bf16 v[88:91], v[140:143], v[180:183], v[88:91]
	v_mfma_f32_16x16x32_bf16 v[76:79], v[132:135], v[188:191], v[76:79]
	v_mfma_f32_16x16x32_bf16 v[72:75], v[140:143], v[188:191], v[72:75]
	s_setprio 0
	s_setprio 1
	v_mfma_f32_16x16x32_bf16 v[116:119], v[144:147], v[160:163], v[116:119]
	v_mfma_f32_16x16x32_bf16 v[112:115], v[152:155], v[160:163], v[112:115]
	v_mfma_f32_16x16x32_bf16 v[100:103], v[144:147], v[168:171], v[100:103]
	v_mfma_f32_16x16x32_bf16 v[96:99], v[152:155], v[168:171], v[96:99]
	v_mfma_f32_16x16x32_bf16 v[84:87], v[144:147], v[176:179], v[84:87]
	v_mfma_f32_16x16x32_bf16 v[80:83], v[152:155], v[176:179], v[80:83]
	v_mfma_f32_16x16x32_bf16 v[68:71], v[144:147], v[184:187], v[68:71]
	v_mfma_f32_16x16x32_bf16 v[64:67], v[152:155], v[184:187], v[64:67]
	v_mfma_f32_16x16x32_bf16 v[116:119], v[148:151], v[164:167], v[116:119]
	v_mfma_f32_16x16x32_bf16 v[112:115], v[156:159], v[164:167], v[112:115]
	v_mfma_f32_16x16x32_bf16 v[100:103], v[148:151], v[172:175], v[100:103]
	v_mfma_f32_16x16x32_bf16 v[96:99], v[156:159], v[172:175], v[96:99]
	v_mfma_f32_16x16x32_bf16 v[84:87], v[148:151], v[180:183], v[84:87]
	v_mfma_f32_16x16x32_bf16 v[80:83], v[156:159], v[180:183], v[80:83]
	v_mfma_f32_16x16x32_bf16 v[68:71], v[148:151], v[188:191], v[68:71]
	v_mfma_f32_16x16x32_bf16 v[64:67], v[156:159], v[188:191], v[64:67]
	s_setprio 0
	s_barrier
	s_add_i32 s90, s92, s33
	s_mov_b32 m0, s90
	ds_read_b128 v[160:163], v205 offset:16384
	ds_read_b128 v[164:167], v205 offset:17408
	ds_read_b128 v[168:171], v205 offset:18432
	ds_read_b128 v[172:175], v205 offset:19456
	ds_read_b128 v[176:179], v205 offset:20480
	ds_read_b128 v[180:183], v205 offset:21504
	ds_read_b128 v[184:187], v205 offset:22528
	ds_read_b128 v[188:191], v205 offset:23552
	global_load_lds_dwordx4 v249, s[98:99] nt
	s_add_i32 m0, s90, 0x2000
	s_nop 0
	global_load_lds_dwordx4 v249, s[100:101] nt
	s_add_i32 s22, s93, s33
	s_mov_b32 m0, s22
	s_nop 0
	s_add_u32 s98, s98, 0x10000
	s_addc_u32 s99, s99, 0
	s_add_u32 s100, s100, 0x10000
	s_addc_u32 s101, s101, 0
	global_load_lds_dwordx4 v249, s[98:99] nt
	s_add_i32 m0, s22, 0x2000
	s_nop 0
	global_load_lds_dwordx4 v249, s[100:101] nt
	s_mov_b32 m0, s73
	s_nop 0
	s_add_u32 s98, s98, 0x10000
	s_addc_u32 s99, s99, 0
	s_add_u32 s100, s100, 0x10000
	s_addc_u32 s101, s101, 0
	global_load_lds_dwordx4 v249, s[98:99] nt
	s_mov_b32 m0, s34
	s_nop 0
	global_load_lds_dwordx4 v249, s[100:101] nt
	s_waitcnt vmcnt(8)
	s_waitcnt lgkmcnt(0)
	s_barrier
;     __device__ __forceinline__ void operator()(f32x4 (&acc)[2][2][4][2], const Unit& u, int wr, int wc, int fr, int fq) const {
;     ...
;                 for (int m = 0; m < 4; ++m) { const size_t off = (size_t)(row0 + ai * HALF + m * 16) * ldc + col0;
; #pragma unroll
;                     for (int bj = 0; bj < 2; ++bj) bv[ai][m][bj] = __builtin_nontemporal_load((const u32x4*)(hb + off + bj * HALF)); }
	s_setprio 1
	s_waitcnt lgkmcnt(0)
	v_mfma_f32_16x16x32_bf16 v[60:63], v[128:131], v[160:163], v[60:63]
	v_mfma_f32_16x16x32_bf16 v[56:59], v[136:139], v[160:163], v[56:59]
	v_mfma_f32_16x16x32_bf16 v[44:47], v[128:131], v[168:171], v[44:47]
	v_mfma_f32_16x16x32_bf16 v[40:43], v[136:139], v[168:171], v[40:43]
	v_mfma_f32_16x16x32_bf16 v[28:31], v[128:131], v[176:179], v[28:31]
	v_mfma_f32_16x16x32_bf16 v[24:27], v[136:139], v[176:179], v[24:27]
	v_mfma_f32_16x16x32_bf16 v[12:15], v[128:131], v[184:187], v[12:15]
	v_mfma_f32_16x16x32_bf16 v[8:11], v[136:139], v[184:187], v[8:11]
	v_mfma_f32_16x16x32_bf16 v[60:63], v[132:135], v[164:167], v[60:63]
	v_mfma_f32_16x16x32_bf16 v[56:59], v[140:143], v[164:167], v[56:59]
	v_mfma_f32_16x16x32_bf16 v[44:47], v[132:135], v[172:175], v[44:47]
	v_mfma_f32_16x16x32_bf16 v[40:43], v[140:143], v[172:175], v[40:43]
	v_mfma_f32_16x16x32_bf16 v[28:31], v[132:135], v[180:183], v[28:31]
	v_mfma_f32_16x16x32_bf16 v[24:27], v[140:143], v[180:183], v[24:27]
	v_mfma_f32_16x16x32_bf16 v[12:15], v[132:135], v[188:191], v[12:15]
	v_mfma_f32_16x16x32_bf16 v[8:11], v[140:143], v[188:191], v[8:11]
	s_setprio 0
	s_setprio 1
	v_mfma_f32_16x16x32_bf16 v[52:55], v[144:147], v[160:163], v[52:55]
	v_mfma_f32_16x16x32_bf16 v[48:51], v[152:155], v[160:163], v[48:51]
	v_mfma_f32_16x16x32_bf16 v[36:39], v[144:147], v[168:171], v[36:39]
	v_mfma_f32_16x16x32_bf16 v[32:35], v[152:155], v[168:171], v[32:35]
	v_mfma_f32_16x16x32_bf16 v[20:23], v[144:147], v[176:179], v[20:23]
	v_mfma_f32_16x16x32_bf16 v[16:19], v[152:155], v[176:179], v[16:19]
	v_mfma_f32_16x16x32_bf16 v[4:7], v[144:147], v[184:187], v[4:7]
	v_mfma_f32_16x16x32_bf16 v[0:3], v[152:155], v[184:187], v[0:3]
	v_mfma_f32_16x16x32_bf16 v[52:55], v[148:151], v[164:167], v[52:55]
	v_mfma_f32_16x16x32_bf16 v[48:51], v[156:159], v[164:167], v[48:51]
	v_mfma_f32_16x16x32_bf16 v[36:39], v[148:151], v[172:175], v[36:39]
	v_mfma_f32_16x16x32_bf16 v[32:35], v[156:159], v[172:175], v[32:35]
	v_mfma_f32_16x16x32_bf16 v[20:23], v[148:151], v[180:183], v[20:23]
	v_mfma_f32_16x16x32_bf16 v[16:19], v[156:159], v[180:183], v[16:19]
	v_mfma_f32_16x16x32_bf16 v[4:7], v[148:151], v[188:191], v[4:7]
	v_mfma_f32_16x16x32_bf16 v[0:3], v[156:159], v[188:191], v[0:3]
	s_setprio 0
	s_barrier
	s_add_i32 s22, 0, 0x18000
	s_add_i32 s23, 0, 0x1c000
	v_add_u32_e32 v140, s22, v203
	v_add_u32_e32 v156, s23, v203
	ds_read_b128 v[128:131], v140
	ds_read_b128 v[132:135], v140 offset:1024
	ds_read_b128 v[136:139], v140 offset:2048
	ds_read_b128 v[140:143], v140 offset:3072
	ds_read_b128 v[144:147], v156
	ds_read_b128 v[148:151], v156 offset:1024
	ds_read_b128 v[152:155], v156 offset:2048
	ds_read_b128 v[156:159], v156 offset:3072
	s_mov_b32 m0, s35
	ds_read_b128 v[160:163], v205 offset:32768
	ds_read_b128 v[164:167], v205 offset:33792
	ds_read_b128 v[168:171], v205 offset:34816
	ds_read_b128 v[172:175], v205 offset:35840
	ds_read_b128 v[176:179], v205 offset:36864
	ds_read_b128 v[180:183], v205 offset:37888
	ds_read_b128 v[184:187], v205 offset:38912
	ds_read_b128 v[188:191], v205 offset:39936
	s_add_u32 s98, s98, 0x10000
	s_addc_u32 s99, s99, 0
	s_add_u32 s100, s100, 0x10000
	s_addc_u32 s101, s101, 0
	global_load_lds_dwordx4 v249, s[98:99] nt
	s_mov_b32 m0, s0
	s_nop 0
	global_load_lds_dwordx4 v249, s[100:101] nt
	s_waitcnt vmcnt(8)
	s_waitcnt lgkmcnt(0)
	s_barrier
	s_setprio 1
	s_waitcnt lgkmcnt(0)
	v_mfma_f32_16x16x32_bf16 v[124:127], v[128:131], v[160:163], v[124:127]
	v_mfma_f32_16x16x32_bf16 v[120:123], v[136:139], v[160:163], v[120:123]
	v_mfma_f32_16x16x32_bf16 v[108:111], v[128:131], v[168:171], v[108:111]
	v_mfma_f32_16x16x32_bf16 v[104:107], v[136:139], v[168:171], v[104:107]
	v_mfma_f32_16x16x32_bf16 v[92:95], v[128:131], v[176:179], v[92:95]
	v_mfma_f32_16x16x32_bf16 v[88:91], v[136:139], v[176:179], v[88:91]
	v_mfma_f32_16x16x32_bf16 v[76:79], v[128:131], v[184:187], v[76:79]
	v_mfma_f32_16x16x32_bf16 v[72:75], v[136:139], v[184:187], v[72:75]
	v_mfma_f32_16x16x32_bf16 v[124:127], v[132:135], v[164:167], v[124:127]
	v_mfma_f32_16x16x32_bf16 v[120:123], v[140:143], v[164:167], v[120:123]
	v_mfma_f32_16x16x32_bf16 v[108:111], v[132:135], v[172:175], v[108:111]
	v_mfma_f32_16x16x32_bf16 v[104:107], v[140:143], v[172:175], v[104:107]
	v_mfma_f32_16x16x32_bf16 v[92:95], v[132:135], v[180:183], v[92:95]
	v_mfma_f32_16x16x32_bf16 v[88:91], v[140:143], v[180:183], v[88:91]
	v_mfma_f32_16x16x32_bf16 v[76:79], v[132:135], v[188:191], v[76:79]
	v_mfma_f32_16x16x32_bf16 v[72:75], v[140:143], v[188:191], v[72:75]
	s_setprio 0
	s_setprio 1
	v_mfma_f32_16x16x32_bf16 v[116:119], v[144:147], v[160:163], v[116:119]
	v_mfma_f32_16x16x32_bf16 v[112:115], v[152:155], v[160:163], v[112:115]
	v_mfma_f32_16x16x32_bf16 v[100:103], v[144:147], v[168:171], v[100:103]
	v_mfma_f32_16x16x32_bf16 v[96:99], v[152:155], v[168:171], v[96:99]
	v_mfma_f32_16x16x32_bf16 v[84:87], v[144:147], v[176:179], v[84:87]
	v_mfma_f32_16x16x32_bf16 v[80:83], v[152:155], v[176:179], v[80:83]
	v_mfma_f32_16x16x32_bf16 v[68:71], v[144:147], v[184:187], v[68:71]
	v_mfma_f32_16x16x32_bf16 v[64:67], v[152:155], v[184:187], v[64:67]
	v_mfma_f32_16x16x32_bf16 v[116:119], v[148:151], v[164:167], v[116:119]
	v_mfma_f32_16x16x32_bf16 v[112:115], v[156:159], v[164:167], v[112:115]
	v_mfma_f32_16x16x32_bf16 v[100:103], v[148:151], v[172:175], v[100:103]
	v_mfma_f32_16x16x32_bf16 v[96:99], v[156:159], v[172:175], v[96:99]
	v_mfma_f32_16x16x32_bf16 v[84:87], v[148:151], v[180:183], v[84:87]
	v_mfma_f32_16x16x32_bf16 v[80:83], v[156:159], v[180:183], v[80:83]
	v_mfma_f32_16x16x32_bf16 v[68:71], v[148:151], v[188:191], v[68:71]
	v_mfma_f32_16x16x32_bf16 v[64:67], v[156:159], v[188:191], v[64:67]
	s_setprio 0
	s_barrier
;     __device__ __forceinline__ void operator()(f32x4 (&acc)[2][2][4][2], const Unit& u, int wr, int wc, int fr, int fq) const {
;     ...
;                 for (int m = 0; m < 4; ++m) { const size_t off = (size_t)(row0 + ai * HALF + m * 16) * ldc + col0;
; #pragma unroll
;                     for (int bj = 0; bj < 2; ++bj) bv[ai][m][bj] = __builtin_nontemporal_load((const u32x4*)(hb + off + bj * HALF)); }
	s_add_i32 s22, s22, s33
	s_mov_b32 m0, s22
	ds_read_b128 v[160:163], v205 offset:49152
	ds_read_b128 v[164:167], v205 offset:50176
	ds_read_b128 v[168:171], v205 offset:51200
	ds_read_b128 v[172:175], v205 offset:52224
	ds_read_b128 v[176:179], v205 offset:53248
	ds_read_b128 v[180:183], v205 offset:54272
	ds_read_b128 v[184:187], v205 offset:55296
	ds_read_b128 v[188:191], v205 offset:56320
	s_add_u32 s98, s98, 0x50000
	s_addc_u32 s99, s99, 0
	s_add_u32 s100, s100, 0x50000
	s_addc_u32 s101, s101, 0
	global_load_lds_dwordx4 v249, s[98:99] nt
	s_add_i32 m0, s22, 0x2000
	s_add_i32 s22, s23, s33
	global_load_lds_dwordx4 v249, s[100:101] nt
	s_mov_b32 m0, s22
	s_nop 0
	s_add_u32 s98, s98, 0x10000
	s_addc_u32 s99, s99, 0
	s_add_u32 s100, s100, 0x10000
	s_addc_u32 s101, s101, 0
	global_load_lds_dwordx4 v249, s[98:99] nt
	s_add_i32 m0, s22, 0x2000
	s_nop 0
	global_load_lds_dwordx4 v249, s[100:101] nt
	s_mov_b32 m0, s1
	s_nop 0
	s_add_u32 s98, s98, 0x10000
	s_addc_u32 s99, s99, 0
	s_add_u32 s100, s100, 0x10000
	s_addc_u32 s101, s101, 0
	global_load_lds_dwordx4 v249, s[98:99] nt
	s_mov_b32 m0, s54
	s_nop 0
	global_load_lds_dwordx4 v249, s[100:101] nt
	s_waitcnt vmcnt(8)
	s_waitcnt lgkmcnt(0)
	s_barrier
	s_setprio 1
	s_waitcnt lgkmcnt(0)
	v_mfma_f32_16x16x32_bf16 v[60:63], v[128:131], v[160:163], v[60:63]
	v_mfma_f32_16x16x32_bf16 v[56:59], v[136:139], v[160:163], v[56:59]
	v_mfma_f32_16x16x32_bf16 v[44:47], v[128:131], v[168:171], v[44:47]
	v_mfma_f32_16x16x32_bf16 v[40:43], v[136:139], v[168:171], v[40:43]
	v_mfma_f32_16x16x32_bf16 v[28:31], v[128:131], v[176:179], v[28:31]
	v_mfma_f32_16x16x32_bf16 v[24:27], v[136:139], v[176:179], v[24:27]
	v_mfma_f32_16x16x32_bf16 v[12:15], v[128:131], v[184:187], v[12:15]
	v_mfma_f32_16x16x32_bf16 v[8:11], v[136:139], v[184:187], v[8:11]
	v_mfma_f32_16x16x32_bf16 v[60:63], v[132:135], v[164:167], v[60:63]
	v_mfma_f32_16x16x32_bf16 v[56:59], v[140:143], v[164:167], v[56:59]
	v_mfma_f32_16x16x32_bf16 v[44:47], v[132:135], v[172:175], v[44:47]
	v_mfma_f32_16x16x32_bf16 v[40:43], v[140:143], v[172:175], v[40:43]
	v_mfma_f32_16x16x32_bf16 v[28:31], v[132:135], v[180:183], v[28:31]
	v_mfma_f32_16x16x32_bf16 v[24:27], v[140:143], v[180:183], v[24:27]
	v_mfma_f32_16x16x32_bf16 v[12:15], v[132:135], v[188:191], v[12:15]
	v_mfma_f32_16x16x32_bf16 v[8:11], v[140:143], v[188:191], v[8:11]
	s_setprio 0
	s_setprio 1
	v_mfma_f32_16x16x32_bf16 v[52:55], v[144:147], v[160:163], v[52:55]
	v_mfma_f32_16x16x32_bf16 v[48:51], v[152:155], v[160:163], v[48:51]
	v_mfma_f32_16x16x32_bf16 v[36:39], v[144:147], v[168:171], v[36:39]
	v_mfma_f32_16x16x32_bf16 v[32:35], v[152:155], v[168:171], v[32:35]
	v_mfma_f32_16x16x32_bf16 v[20:23], v[144:147], v[176:179], v[20:23]
	v_mfma_f32_16x16x32_bf16 v[16:19], v[152:155], v[176:179], v[16:19]
	v_mfma_f32_16x16x32_bf16 v[4:7], v[144:147], v[184:187], v[4:7]
	v_mfma_f32_16x16x32_bf16 v[0:3], v[152:155], v[184:187], v[0:3]
	v_mfma_f32_16x16x32_bf16 v[52:55], v[148:151], v[164:167], v[52:55]
	v_mfma_f32_16x16x32_bf16 v[48:51], v[156:159], v[164:167], v[48:51]
	v_mfma_f32_16x16x32_bf16 v[36:39], v[148:151], v[172:175], v[36:39]
	v_mfma_f32_16x16x32_bf16 v[32:35], v[156:159], v[172:175], v[32:35]
	v_mfma_f32_16x16x32_bf16 v[20:23], v[148:151], v[180:183], v[20:23]
	v_mfma_f32_16x16x32_bf16 v[16:19], v[156:159], v[180:183], v[16:19]
	v_mfma_f32_16x16x32_bf16 v[4:7], v[148:151], v[188:191], v[4:7]
	v_mfma_f32_16x16x32_bf16 v[0:3], v[156:159], v[188:191], v[0:3]
	s_setprio 0
	s_barrier
	s_add_u32 s98, s98, 0x10000
	s_addc_u32 s99, s99, 0
	s_add_u32 s100, s100, 0x10000
	s_addc_u32 s101, s101, 0
	s_add_i32 m0, s73, 0xc000
	s_nop 0
	global_load_lds_dwordx4 v249, s[98:99] nt
	s_add_i32 m0, s73, 0xe000
	s_nop 0
	global_load_lds_dwordx4 v249, s[100:101] nt
	s_add_i32 s89, s89, 2
	s_add_u32 vcc_lo, vcc_lo, 0x100
	s_addc_u32 s88, s88, 0
	s_mov_b64 s[20:21], s[42:43]
